# e14 plus forgetting-attention dynamic queue: the next unit index is popped one unit ahead (atomic issued at the start of the previous unit) so the pop round trip is off the unit-start critical path
# speedup vs baseline: 1.0031x; 1.0031x over previous
.LBB0_133:
	s_add_u32 s28, s46, 0x17400000
	s_addc_u32 s29, s47, 0
	s_add_u32 s0, s46, 0x1c0000
	s_addc_u32 s1, s47, 0
	v_writelane_b32 v255, s0, 56
	s_add_u32 s52, s46, 0x180000
	s_addc_u32 s53, s47, 0
	v_writelane_b32 v255, s1, 57
	v_mbcnt_lo_u32_b32 v0, -1, 0
	v_mbcnt_hi_u32_b32 v0, -1, v0
	s_nop 0
	v_or_b32_e32 v0, s33, v0
	v_cmp_eq_u32_e32 vcc, 0, v0
	s_and_saveexec_b64 s[98:99], vcc
	s_cbranch_execz .Lmy_popinit
	v_mov_b32_e32 v2, 1
	global_atomic_add v248, v1, v2, s[0:1] sc0
.Lmy_popinit:
	s_or_b64 exec, exec, s[98:99]
	s_add_i32 s30, s42, 0xfffffeff
	s_waitcnt lgkmcnt(0)
	s_barrier
	s_branch .LBB0_136

.LBB0_136:
	v_mbcnt_lo_u32_b32 v0, -1, 0
	v_mbcnt_hi_u32_b32 v0, -1, v0
	s_nop 0
	v_or_b32_e32 v0, s33, v0
	v_cmp_eq_u32_e32 vcc, 0, v0
	s_and_saveexec_b64 s[0:1], vcc
	s_cbranch_execz .LBB0_140
	s_mov_b64 s[4:5], exec
	v_mbcnt_lo_u32_b32 v0, s4, 0
	v_mbcnt_hi_u32_b32 v0, s5, v0
	v_cmp_eq_u32_e32 vcc, 0, v0
	s_and_saveexec_b64 s[2:3], vcc
	s_cbranch_execz .LBB0_139
	s_bcnt1_i32_b64 s4, s[4:5]
	v_mov_b32_e32 v2, s4
	v_readlane_b32 s4, v255, 56
	v_readlane_b32 s5, v255, 57
	s_waitcnt vmcnt(0)
	v_mov_b32_e32 v250, v248
	s_nop 3
	global_atomic_add v248, v1, v2, s[4:5] sc0
	v_mov_b32_e32 v2, v250
.LBB0_139:
	s_or_b64 exec, exec, s[2:3]
	v_readfirstlane_b32 s2, v2
	s_nop 1
	v_add_u32_e32 v0, s2, v0
	v_readlane_b32 s2, v255, 11
	s_nop 1
	v_mov_b32_e32 v2, s2
	ds_write_b32 v2, v0
